# v03 + CVX 5000->3200 (fewer conversion items beside the scan jobs; branch tail stays 6 rounds)
# speedup vs baseline: 1.0009x; 1.0009x over previous
.LBB0_80:
	v_readlane_b32 s22, v248, 1
	v_readlane_b32 s23, v248, 2
	s_add_u32 s0, s22, 0x72d00000
	s_addc_u32 s1, s23, 0
	v_writelane_b32 v249, s0, 4
	v_readlane_b32 s24, v248, 7
	v_readlane_b32 s48, v248, 26
	v_writelane_b32 v249, s1, 5
	s_ashr_i32 s0, s24, 31
	v_readlane_b32 s50, v248, 28
	v_writelane_b32 v249, s0, 6
	v_readlane_b32 s51, v248, 29
	s_add_u32 s0, s50, 0x2000
	s_addc_u32 s1, s51, 0
	v_writelane_b32 v249, s0, 7
	s_cmpk_lg_i32 s24, 0x100
	v_readlane_b32 s13, v248, 43
	v_writelane_b32 v249, s1, 8
	s_cselect_b64 s[0:1], -1, 0
	v_writelane_b32 v249, s0, 9
	s_cmpk_lt_i32 s13, 0x1400
	v_readlane_b32 s21, v248, 0
	v_writelane_b32 v249, s1, 10
	s_cselect_b64 s[0:1], -1, 0
	v_writelane_b32 v249, s0, 11
	v_readlane_b32 s49, v248, 27
	v_mov_b32_e32 v34, 0
	v_writelane_b32 v249, s1, 12
	s_add_i32 s0, s13, 0x3c80
	s_add_u32 s9, s22, 0x24500000
	s_addc_u32 s12, s23, 0
	s_add_u32 s5, s22, 0x1e500000
	v_writelane_b32 v249, s0, 13
	s_addc_u32 s11, s23, 0
	s_add_i32 s0, s21, 0xffffff97
	s_cmpk_lt_u32 s0, 0x67
	s_cselect_b64 s[0:1], -1, 0
	v_writelane_b32 v249, s0, 14
	v_mov_b32_e32 v219, 1
	v_mov_b32_e32 v222, 0x358637bd
	v_writelane_b32 v249, s1, 15
	s_add_i32 s0, s13, 0xfffffcb8
	s_cmpk_lt_i32 s0, 0x1400
	s_cselect_b64 s[0:1], -1, 0
	v_writelane_b32 v249, s0, 16
	v_mov_b32_e32 v223, 0x260
	v_mov_b32_e32 v224, 0x3ecc95a3
	v_writelane_b32 v249, s1, 17
	s_add_i32 s0, s13, 0x3938
	v_writelane_b32 v249, s0, 18
	s_add_u32 s0, s22, 0x4200
	s_addc_u32 s1, s23, 0
	v_writelane_b32 v249, s0, 19
	v_mov_b32_e32 v225, 0x3e2aaaab
	v_mov_b64_e32 v[164:165], 0x969
	v_writelane_b32 v249, s1, 20
	s_add_u32 s0, s22, 0x4400
	s_addc_u32 s1, s23, 0
	v_writelane_b32 v249, s0, 21
	v_mov_b64_e32 v[166:167], 0x968
	v_mov_b32_e32 v226, 0x41b17218
	v_writelane_b32 v249, s1, 22
	s_add_u32 s0, s22, 0x4500
	s_addc_u32 s1, s23, 0
	v_writelane_b32 v249, s0, 23
	v_mov_b64_e32 v[168:169], 0x630
	v_mov_b64_e32 v[170:171], 0x62f
	v_writelane_b32 v249, s1, 24
	s_add_u32 s0, s22, 0x4600
	s_addc_u32 s1, s23, 0
	v_writelane_b32 v249, s0, 25
	v_mov_b32_e32 v227, 0x1e040
	v_mov_b32_e32 v228, 2
	v_writelane_b32 v249, s1, 26
	s_add_u32 s0, s22, 0x4700
	s_addc_u32 s1, s23, 0
	v_writelane_b32 v249, s0, 27
	v_mov_b32_e32 v230, 0x3000
	v_mov_b32_e32 v231, 0x7f800000
	v_writelane_b32 v249, s1, 28
	s_add_u32 s0, s22, 0x4800
	s_addc_u32 s1, s23, 0
	v_writelane_b32 v249, s0, 29
	v_readlane_b32 s52, v248, 30
	v_readlane_b32 s53, v248, 31
	v_writelane_b32 v249, s1, 30
	s_add_u32 s0, s22, 0x4900
	s_addc_u32 s1, s23, 0
	v_writelane_b32 v249, s0, 31
	v_readlane_b32 s54, v248, 32
	v_readlane_b32 s55, v248, 33
	v_writelane_b32 v249, s1, 32
	s_add_u32 s0, s22, 0x4a00
	s_addc_u32 s1, s23, 0
	v_writelane_b32 v249, s0, 33
	v_readlane_b32 s56, v248, 34
	v_readlane_b32 s57, v248, 35
	v_writelane_b32 v249, s1, 34
	s_add_u32 s0, s22, 0x4b00
	s_addc_u32 s1, s23, 0
	v_writelane_b32 v249, s0, 35
	v_readlane_b32 s58, v248, 36
	v_readlane_b32 s59, v248, 37
	v_writelane_b32 v249, s1, 36
	s_add_u32 s0, s22, 0x4c00
	s_addc_u32 s1, s23, 0
	v_writelane_b32 v249, s0, 37
	v_readlane_b32 s60, v248, 38
	v_readlane_b32 s61, v248, 39
	v_writelane_b32 v249, s1, 38
	s_add_u32 s0, s22, 0x4d00
	s_addc_u32 s1, s23, 0
	v_writelane_b32 v249, s0, 39
	v_readlane_b32 s62, v248, 40
	v_readlane_b32 s63, v248, 41
	v_writelane_b32 v249, s1, 40
	s_add_u32 s0, s22, 0x4e00
	s_addc_u32 s1, s23, 0
	v_writelane_b32 v249, s0, 41
	s_nop 1
	v_writelane_b32 v249, s1, 42
	s_add_u32 s0, s22, 0x4f00
	s_addc_u32 s1, s23, 0
	v_writelane_b32 v249, s0, 43
	s_nop 1
	v_writelane_b32 v249, s1, 44
	s_add_u32 s0, s22, 0x5000
	s_addc_u32 s1, s23, 0
	v_writelane_b32 v249, s0, 45
	s_nop 1
	v_writelane_b32 v249, s1, 46
	s_add_u32 s0, s22, 0x5100
	s_addc_u32 s1, s23, 0
	v_writelane_b32 v249, s0, 47
	s_nop 1
	v_writelane_b32 v249, s1, 48
	s_add_u32 s0, s22, 0x5200
	s_addc_u32 s1, s23, 0
	v_writelane_b32 v249, s0, 49
	s_nop 1
	v_writelane_b32 v249, s1, 50
	s_add_u32 s0, s22, 0x5300
	s_addc_u32 s1, s23, 0
	v_writelane_b32 v249, s0, 51
	s_cmp_eq_u32 s46, 15
	s_nop 0
	v_writelane_b32 v249, s1, 52
	s_cselect_b64 s[0:1], -1, 0
	v_writelane_b32 v249, s0, 53
	s_cmp_eq_u32 s46, 14
	s_nop 0
	v_writelane_b32 v249, s1, 54
	s_cselect_b64 s[0:1], -1, 0
	v_writelane_b32 v249, s0, 55
	s_cmp_eq_u32 s46, 13
	s_nop 0
	v_writelane_b32 v249, s1, 56
	s_cselect_b64 s[0:1], -1, 0
	v_writelane_b32 v249, s0, 57
	s_cmp_eq_u32 s46, 12
	s_nop 0
	v_writelane_b32 v249, s1, 58
	s_cselect_b64 s[0:1], -1, 0
	v_writelane_b32 v249, s0, 59
	s_cmp_eq_u32 s46, 11
	s_nop 0
	v_writelane_b32 v249, s1, 60
	s_cselect_b64 s[0:1], -1, 0
	v_writelane_b32 v249, s0, 61
	s_cmp_eq_u32 s46, 10
	s_nop 0
	v_writelane_b32 v249, s1, 62
	s_cselect_b64 s[0:1], -1, 0
	v_writelane_b32 v249, s0, 63
	s_cmp_eq_u32 s46, 9
	s_nop 0
	v_writelane_b32 v250, s1, 0
	s_cselect_b64 s[0:1], -1, 0
	v_writelane_b32 v250, s0, 1
	s_cmp_eq_u32 s46, 8
	s_nop 0
	v_writelane_b32 v250, s1, 2
	s_cselect_b64 s[0:1], -1, 0
	v_writelane_b32 v250, s0, 3
	s_cmp_eq_u32 s46, 7
	s_nop 0
	v_writelane_b32 v250, s1, 4
	s_cselect_b64 s[0:1], -1, 0
	v_writelane_b32 v250, s0, 5
	s_cmp_eq_u32 s46, 6
	s_nop 0
	v_writelane_b32 v250, s1, 6
	s_cselect_b64 s[0:1], -1, 0
	v_writelane_b32 v250, s0, 7
	s_cmp_eq_u32 s46, 5
	s_nop 0
	v_writelane_b32 v250, s1, 8
	s_cselect_b64 s[0:1], -1, 0
	v_writelane_b32 v250, s0, 9
	s_cmp_eq_u32 s46, 4
	s_nop 0
	v_writelane_b32 v250, s1, 10
	s_cselect_b64 s[0:1], -1, 0
	v_writelane_b32 v250, s0, 11
	s_cmp_eq_u32 s46, 3
	s_nop 0
	v_writelane_b32 v250, s1, 12
	s_cselect_b64 s[0:1], -1, 0
	v_writelane_b32 v250, s0, 13
	s_cmp_eq_u32 s46, 2
	s_nop 0
	v_writelane_b32 v250, s1, 14
	s_cselect_b64 s[0:1], -1, 0
	v_writelane_b32 v250, s0, 15
	s_cmp_eq_u32 s46, 1
	s_nop 0
	v_writelane_b32 v250, s1, 16
	s_cselect_b64 s[0:1], -1, 0
	v_writelane_b32 v250, s0, 17
	s_cmp_eq_u32 s46, 0
	s_nop 0
	v_writelane_b32 v250, s1, 18
	s_cselect_b64 s[0:1], -1, 0
	v_writelane_b32 v250, s0, 19
	s_nop 1
	v_writelane_b32 v250, s1, 20
	s_lshl_b32 s0, s46, 8
	s_add_u32 s0, s2, s0
	s_addc_u32 s1, s3, 0
	s_add_u32 s2, s0, 0x1400
	s_addc_u32 s3, s1, 0
	v_writelane_b32 v250, s2, 21
	s_add_u32 s0, s0, 0x2400
	s_addc_u32 s1, s1, 0
	v_writelane_b32 v250, s3, 22
	v_writelane_b32 v250, s0, 23
	s_nop 1
	v_writelane_b32 v250, s1, 24
	s_add_u32 s0, s22, 0x7400
	s_addc_u32 s1, s23, 0
	v_writelane_b32 v250, s0, 25
	s_nop 1
	v_writelane_b32 v250, s1, 26
	s_add_u32 s0, s22, 0x7500
	s_addc_u32 s1, s23, 0
	v_writelane_b32 v250, s0, 27
	s_cmpk_lt_i32 s21, 0x220
	s_nop 0
	v_writelane_b32 v250, s1, 28
	s_cselect_b64 s[0:1], -1, 0
	v_writelane_b32 v250, s0, 29
	s_ashr_i32 s14, s21, 31
	s_add_i32 s8, s21, 0xffffff40
	v_writelane_b32 v250, s1, 30
	s_lshr_b32 s0, s14, 26
	s_add_i32 s0, s21, s0
	s_ashr_i32 s7, s0, 6
	s_add_i32 s0, s24, 0xffffff40
	v_writelane_b32 v250, s0, 31
	s_sub_i32 s0, s21, 64
	s_cmpk_lt_i32 s21, 0x80
	s_cselect_b32 s25, s21, s0
	s_cmpk_lt_i32 s25, 0x220
	v_writelane_b32 v250, s0, 32
	s_cselect_b64 s[0:1], -1, 0
	v_writelane_b32 v250, s0, 33
	s_nop 1
	v_writelane_b32 v250, s1, 34
	s_add_u32 s0, s22, 0x12000
	v_writelane_b32 v250, s0, 35
	s_addc_u32 s0, s23, 0
	v_writelane_b32 v250, s0, 36
	s_add_i32 s0, s21, 0xffffff80
	v_writelane_b32 v250, s0, 37
	s_add_i32 s0, s21, 1
	v_writelane_b32 v250, s0, 38
	s_sub_i32 s0, s21, 63
	v_writelane_b32 v250, s0, 39
	s_add_i32 s0, s21, 0xffffff81
	s_cmpk_gt_i32 s21, 0xbf
	v_writelane_b32 v250, s0, 40
	s_cselect_b64 s[0:1], -1, 0
	s_cmpk_eq_i32 s24, 0x100
	s_cselect_b64 s[26:27], -1, 0
	s_and_b64 s[2:3], s[26:27], exec
	s_movk_i32 s2, 0x200
	s_cselect_b32 s6, s2, 0x210
	s_movk_i32 s2, 0x2000
	s_cselect_b32 s2, s2, 0x2100
	v_writelane_b32 v250, s2, 41
	s_cselect_b32 s19, 32, 33
	s_cselect_b32 s10, 0xc80, 0
	s_and_b64 s[0:1], s[0:1], s[26:27]
	v_writelane_b32 v250, s0, 42
	s_nop 1
	v_writelane_b32 v250, s1, 43
	s_add_u32 s0, s22, 0x10000
	v_writelane_b32 v250, s0, 44
	s_addc_u32 s0, s23, 0
	v_writelane_b32 v250, s0, 45
	s_lshl_b32 s0, s8, 3
	s_add_i32 s15, s33, s0
	s_cmpk_lt_i32 s21, 0xf0
	s_mul_hi_i32 s0, s8, 0x55555556
	s_cselect_b64 s[2:3], -1, 0
	s_lshr_b32 s1, s0, 31
	s_add_i32 s1, s0, s1
	s_mul_i32 s0, s1, -3
	v_writelane_b32 v250, s2, 46
	s_add_i32 s0, s0, s8
	s_mul_i32 s4, s1, 0x300000
	v_writelane_b32 v250, s3, 47
	s_lshl_b32 s2, s0, 11
	s_ashr_i32 s3, s2, 31
	s_lshl_b64 s[28:29], s[2:3], 1
	s_add_u32 s2, s5, s28
	v_writelane_b32 v250, s5, 48
	s_addc_u32 s3, s11, s29
	v_writelane_b32 v250, s11, 49
	s_add_u32 s2, s2, s4
	s_mul_hi_i32 s5, s1, 0x300000
	v_writelane_b32 v250, s2, 50
	s_addc_u32 s2, s3, s5
	v_writelane_b32 v250, s2, 51
	s_lshl_b32 s1, s1, 8
	v_writelane_b32 v250, s1, 52
	s_ashr_i32 s1, s0, 31
	s_lshl_b64 s[2:3], s[0:1], 12
	v_writelane_b32 v250, s2, 53
	s_lshl_b64 s[0:1], s[0:1], 22
	s_ashr_i32 s8, s8, 2
	v_writelane_b32 v250, s3, 54
	v_writelane_b32 v250, s0, 55
	s_nop 1
	v_writelane_b32 v250, s1, 56
	s_and_b32 s0, s21, 3
	s_lshl_b32 s2, s0, 10
	s_lshl_b32 s30, s0, 11
	v_writelane_b32 v250, s9, 57
	s_add_u32 s11, s9, s30
	v_writelane_b32 v250, s12, 58
	s_addc_u32 s12, s12, 0
	s_ashr_i32 s9, s8, 31
	s_lshl_b32 s3, s0, 20
	s_lshl_b64 s[0:1], s[8:9], 21
	s_add_u32 s9, s11, s0
	v_writelane_b32 v250, s9, 59
	s_addc_u32 s9, s12, s1
	v_writelane_b32 v250, s9, 60
	s_lshl_b32 s8, s8, 8
	v_writelane_b32 v250, s8, 61
	s_cmpk_lt_i32 s15, 0xc80
	v_writelane_b32 v250, s15, 62
	s_cselect_b64 s[8:9], -1, 0
	v_writelane_b32 v250, s8, 63
	s_nop 1
	v_writelane_b32 v251, s9, 0
	s_add_u32 s8, s48, 0x1e040000
	s_addc_u32 s9, s49, 0
	v_writelane_b32 v251, s8, 1
	v_readlane_b32 s36, v248, 10
	v_readlane_b32 s50, v248, 24
	v_writelane_b32 v251, s9, 2
	s_add_u32 s8, s22, 0xf300000
	s_addc_u32 s9, s23, 0
	s_lshl_b32 s34, s19, 4
	v_writelane_b32 v251, s8, 3
	s_cmp_lt_i32 s21, s34
	v_readlane_b32 s51, v248, 25
	v_writelane_b32 v251, s9, 4
	s_cselect_b64 s[8:9], -1, 0
	v_writelane_b32 v251, s8, 5
	s_add_i32 s16, s24, s6
	s_add_i32 s20, s19, -8
	v_writelane_b32 v251, s9, 6
	s_lshr_b32 s8, s14, 29
	s_add_i32 s8, s21, s8
	v_writelane_b32 v251, s14, 7
	s_ashr_i32 s14, s8, 3
	s_and_b32 s8, s8, -8
	s_sub_i32 s15, s21, s8
	s_add_i32 s17, s16, -1
	s_add_i32 s8, s13, s10
	s_cmpk_lt_i32 s8, 0x3c80
	v_writelane_b32 v251, s8, 8
	s_cselect_b64 s[8:9], -1, 0
	v_writelane_b32 v251, s8, 9
	v_readlane_b32 s48, v248, 22
	v_readlane_b32 s49, v248, 23
	v_writelane_b32 v251, s9, 10
	s_add_u32 s8, s22, 0x85300000
	s_addc_u32 s9, s23, 0
	s_lshl_b32 s31, s19, 1
	v_writelane_b32 v251, s8, 11
	s_add_i32 s18, s10, s33
	s_or_b32 s33, s31, 1
	v_writelane_b32 v251, s9, 12
	s_add_u32 s8, s22, 0x76d00000
	v_writelane_b32 v251, s8, 13
	s_addc_u32 s8, s23, 0
	v_writelane_b32 v251, s8, 14
	s_add_u32 s8, s50, 0x4000
	s_addc_u32 s9, s51, 0
	v_writelane_b32 v251, s8, 15
	v_mov_b32_e32 v1, s15
	v_alignbit_b32 v1, s19, v1, 31
	v_writelane_b32 v251, s9, 16
	s_add_u32 s8, s48, 0x4000
	s_addc_u32 s9, s49, 0
	v_writelane_b32 v251, s8, 17
	v_readlane_b32 s37, v248, 11
	v_readlane_b32 s38, v248, 12
	v_writelane_b32 v251, s9, 18
	v_readlane_b32 s8, v248, 3
	v_readlane_b32 s9, v248, 4
	s_mov_b64 s[12:13], s[8:9]
	s_cmp_gt_i32 s12, 7
	v_readlane_b32 s10, v248, 5
	v_readlane_b32 s11, v248, 6
	s_cselect_b64 s[8:9], -1, 0
	s_cmp_lt_i32 s13, 9
	s_cselect_b64 s[10:11], -1, 0
	s_cmpk_lt_i32 s21, 0xc0
	s_cselect_b32 s7, s7, -1
	s_cmpk_gt_i32 s24, 0xc0
	s_cselect_b32 s7, s7, -2
	s_cmp_lg_u32 s7, 2
	s_cselect_b64 s[12:13], -1, 0
	v_writelane_b32 v251, s26, 19
	s_and_b64 s[12:13], s[26:27], s[12:13]
	s_cmp_lg_u32 s7, 1
	v_writelane_b32 v251, s27, 20
	v_writelane_b32 v251, s12, 21
	v_readlane_b32 s39, v248, 13
	v_readlane_b32 s40, v248, 14
	v_writelane_b32 v251, s13, 22
	v_writelane_b32 v251, s7, 23
	v_readfirstlane_b32 s7, v1
	v_writelane_b32 v251, s19, 24
	s_mul_i32 s7, s7, s15
	s_cselect_b64 s[12:13], -1, 0
	v_writelane_b32 v251, s12, 25
	s_add_i32 s7, s7, s14
	v_readlane_b32 s41, v248, 15
	v_writelane_b32 v251, s13, 26
	s_ashr_i32 s12, s7, 31
	s_lshr_b32 s12, s12, 25
	s_add_i32 s12, s7, s12
	s_ashr_i32 s12, s12, 7
	s_lshl_b32 s13, s12, 7
	s_sub_i32 s7, s7, s13
	s_lshl_b32 s12, s12, 3
	s_cmp_gt_i32 s12, s20
	s_cselect_b32 s13, 1, 8
	s_cmp_lt_i32 s15, 0
	s_cselect_b32 s19, s33, s31
	s_mul_i32 s15, s19, s15
	s_add_i32 s14, s15, s14
	v_cvt_f32_ubyte0_e32 v1, s13
	s_ashr_i32 s15, s14, 31
	v_rcp_iflag_f32_e32 v1, v1
	s_lshr_b32 s15, s15, 25
	s_add_i32 s15, s14, s15
	s_ashr_i32 s15, s15, 7
	s_lshl_b32 s19, s15, 7
	v_mul_f32_e32 v1, 0x4f7ffffe, v1
	v_writelane_b32 v251, s31, 27
	s_sub_i32 s14, s14, s19
	s_lshl_b32 s15, s15, 3
	v_cvt_u32_f32_e32 v1, v1
	v_writelane_b32 v251, s33, 28
	s_cmp_gt_i32 s15, s20
	v_writelane_b32 v251, s20, 29
	s_cselect_b32 s19, 1, 8
	s_or_b64 s[8:9], s[8:9], s[10:11]
	v_writelane_b32 v251, s8, 30
	s_mov_b32 s33, 0xbcf5c28f
	v_readlane_b32 s42, v248, 16
	v_writelane_b32 v251, s9, 31
	s_sub_i32 s8, 0, s13
	v_readfirstlane_b32 s9, v1
	s_mul_i32 s8, s8, s9
	s_mul_hi_u32 s8, s9, s8
	s_add_i32 s9, s9, s8
	s_abs_i32 s8, s7
	s_mul_hi_u32 s9, s8, s9
	s_mul_i32 s10, s9, s13
	s_sub_i32 s8, s8, s10
	s_ashr_i32 s10, s7, 31
	s_add_i32 s11, s9, 1
	s_sub_i32 s20, s8, s13
	s_cmp_ge_u32 s8, s13
	s_cselect_b32 s9, s11, s9
	s_cselect_b32 s8, s20, s8
	s_add_i32 s11, s9, 1
	s_cmp_ge_u32 s8, s13
	s_cselect_b32 s8, s11, s9
	s_xor_b32 s8, s8, s10
	s_sub_i32 s8, s8, s10
	v_writelane_b32 v251, s8, 32
	s_mul_i32 s8, s8, s13
	s_sub_i32 s7, s7, s8
	s_add_i32 s7, s12, s7
	v_writelane_b32 v251, s7, 33
	s_abs_i32 s7, s24
	v_cvt_f32_u32_e32 v1, s7
	s_sub_i32 s8, 0, s7
	v_readlane_b32 s43, v248, 17
	v_readlane_b32 s44, v248, 18
	v_rcp_iflag_f32_e32 v1, v1
	v_readlane_b32 s45, v248, 19
	v_readlane_b32 s46, v248, 20
	v_readlane_b32 s47, v248, 21
	v_mul_f32_e32 v1, 0x4f7ffffe, v1
	v_cvt_u32_f32_e32 v1, v1
	s_nop 0
	v_readfirstlane_b32 s9, v1
	s_mul_i32 s8, s8, s9
	s_mul_hi_u32 s8, s9, s8
	s_add_i32 s9, s9, s8
	s_sub_i32 s8, 1, s16
	s_max_i32 s8, s17, s8
	s_mul_hi_u32 s9, s8, s9
	s_mul_i32 s10, s9, s7
	s_sub_i32 s8, s8, s10
	s_xor_b32 s10, s17, s24
	s_ashr_i32 s10, s10, 31
	s_add_i32 s11, s9, 1
	s_sub_i32 s12, s8, s7
	s_cmp_ge_u32 s8, s7
	s_cselect_b32 s9, s11, s9
	s_cselect_b32 s8, s12, s8
	s_add_i32 s11, s9, 1
	s_cmp_ge_u32 s8, s7
	s_cselect_b32 s7, s11, s9
	s_xor_b32 s7, s7, s10
	s_not_b32 s8, s10
	s_add_i32 s7, s8, s7
	s_mul_i32 s7, s7, s24
	s_sub_i32 s6, s6, s7
	s_sub_i32 s7, s24, s6
	v_cvt_f32_ubyte0_e32 v1, s19
	s_cmp_lt_i32 s7, 1
	v_rcp_iflag_f32_e32 v1, v1
	s_cselect_b64 s[8:9], -1, 0
	v_writelane_b32 v251, s8, 34
	s_cmp_ge_i32 s21, s6
	v_mul_f32_e32 v1, 0x4f7ffffe, v1
	v_writelane_b32 v251, s9, 35
	s_cselect_b64 s[8:9], -1, 0
	s_sub_i32 s6, s21, s6
	v_writelane_b32 v251, s8, 36
	s_lshl_b32 s6, s6, 3
	s_add_i32 s6, s18, s6
	v_writelane_b32 v251, s9, 37
	s_lshl_b32 s7, s7, 3
	v_cvt_u32_f32_e32 v1, v1
	v_writelane_b32 v251, s7, 38
	s_cmpk_lt_i32 s6, 0x3c80
	v_writelane_b32 v251, s6, 39
	s_cselect_b64 s[6:7], -1, 0
	v_writelane_b32 v251, s6, 40
	s_nop 1
	v_writelane_b32 v251, s7, 41
	s_sub_i32 s6, 0, s19
	v_readfirstlane_b32 s7, v1
	s_mul_i32 s6, s6, s7
	s_mul_hi_u32 s6, s7, s6
	s_add_i32 s7, s7, s6
	s_abs_i32 s6, s14
	s_mul_hi_u32 s7, s6, s7
	s_mul_i32 s8, s7, s19
	s_sub_i32 s6, s6, s8
	s_ashr_i32 s8, s14, 31
	s_add_i32 s9, s7, 1
	s_sub_i32 s10, s6, s19
	s_cmp_ge_u32 s6, s19
	s_cselect_b32 s7, s9, s7
	s_cselect_b32 s6, s10, s6
	s_add_i32 s9, s7, 1
	s_cmp_ge_u32 s6, s19
	s_cselect_b32 s6, s9, s7
	s_xor_b32 s6, s6, s8
	s_sub_i32 s8, s6, s8
	s_mul_i32 s6, s8, s19
	s_sub_i32 s6, s14, s6
	s_add_i32 s10, s15, s6
	s_lshl_b32 s6, s21, 8
	v_writelane_b32 v251, s6, 42
	s_lshl_b32 s6, s24, 8
	v_writelane_b32 v251, s6, 43
	v_writelane_b32 v251, s25, 44
	s_lshl_b32 s6, s25, 8
	v_writelane_b32 v251, s6, 45
	s_mov_b32 s6, s10
	s_ashr_i32 s11, s10, 31
	v_writelane_b32 v251, s6, 46
	s_ashr_i32 s9, s8, 31
	v_mbcnt_lo_u32_b32 v1, -1, 0
	v_writelane_b32 v251, s7, 47
	s_lshl_b64 s[6:7], s[10:11], 21
	v_writelane_b32 v251, s6, 48
	v_mbcnt_hi_u32_b32 v229, -1, v1
	s_nop 0
	v_writelane_b32 v251, s7, 49
	s_mov_b32 s6, s8
	v_writelane_b32 v251, s6, 50
	s_nop 1
	v_writelane_b32 v251, s7, 51
	s_lshl_b64 s[6:7], s[8:9], 21
	s_add_u32 s4, s4, s28
	s_addc_u32 s5, s5, s29
	s_add_u32 s4, s22, s4
	v_writelane_b32 v251, s6, 52
	s_addc_u32 s5, s23, s5
	s_add_u32 s4, s4, 0x1e500100
	v_writelane_b32 v251, s7, 53
	v_writelane_b32 v251, s4, 54
	s_addc_u32 s4, s5, 0
	v_writelane_b32 v251, s4, 55
	s_add_u32 s4, s28, 0x55b80080
	v_writelane_b32 v251, s4, 56
	v_writelane_b32 v251, s28, 57
	s_addc_u32 s4, s29, 0
	s_or_b32 s0, s0, s30
	v_writelane_b32 v251, s29, 58
	s_mov_b32 s5, 0
	v_writelane_b32 v251, s4, 59
	s_add_u32 s0, s22, s0
	s_mov_b32 s35, s5
	s_addc_u32 s1, s23, s1
	v_writelane_b32 v251, s34, 60
	s_add_u32 s0, s0, 0x24500100
	s_mov_b64 s[6:7], -1
	v_writelane_b32 v251, s35, 61
	v_writelane_b32 v251, s0, 62
	s_addc_u32 s0, s1, 0
	v_writelane_b32 v251, s0, 63
	s_mul_hi_i32 s1, s66, 0x3000
	s_mul_i32 s0, s66, 0x3000
	v_writelane_b32 v252, s0, 0
	s_ashr_i32 s67, s66, 31
	s_mov_b32 s12, s5
	v_writelane_b32 v252, s1, 1
	s_lshl_b32 s0, s2, 1
	v_writelane_b32 v252, s0, 2
	s_lshl_b32 s0, s3, 2
	v_writelane_b32 v252, s0, 3
	v_writelane_b32 v252, s30, 4
	s_or_b32 s0, s30, 0x6a800080
	v_writelane_b32 v252, s0, 5
	s_add_i32 s0, 0, 0x19800
	v_writelane_b32 v252, s0, 6
	v_cmp_eq_u32_e64 s[0:1], 0, v0
	s_mov_b64 s[2:3], 0x80
	s_nop 0
	v_writelane_b32 v252, s0, 7
	s_nop 1
	v_writelane_b32 v252, s1, 8
	s_lshl_b64 s[0:1], s[66:67], 12
	v_writelane_b32 v252, s0, 9
	s_nop 1
	v_writelane_b32 v252, s1, 10
	s_lshl_b64 s[0:1], s[66:67], 7
	v_writelane_b32 v252, s0, 11
	s_nop 1
	v_writelane_b32 v252, s1, 12
	s_lshl_b64 s[0:1], s[66:67], 13
	v_writelane_b32 v252, s0, 13
	s_nop 1
	v_writelane_b32 v252, s1, 14
	s_mov_b32 s1, 0
	v_writelane_b32 v252, s0, 15
	s_nop 1
	v_writelane_b32 v252, s1, 16
	v_writelane_b32 v252, s66, 17
	s_nop 1
	v_writelane_b32 v252, s67, 18
	s_branch .LBB0_84

.LBB0_1497:
	s_or_b64 exec, exec, s[4:5]
	v_readfirstlane_b32 s4, v0
	s_lshl_b32 s4, s4, 8
	s_and_b32 s4, s4, 0x7fffc000
	s_add_i32 s4, s4, 0
	v_add_u32_e32 v1, s4, v134
	s_waitcnt vmcnt(0)
	v_cvt_pk_bf16_f32 v139, v6, v4
	v_cvt_pk_bf16_f32 v4, v11, v9
	v_cvt_pk_bf16_f32 v5, v7, v5
	v_cvt_pk_bf16_f32 v6, v25, v21
	v_cvt_pk_bf16_f32 v7, v17, v13
	ds_write_b128 v1, v[4:7] offset:128
	v_cvt_pk_bf16_f32 v4, v27, v23
	v_cvt_pk_bf16_f32 v5, v19, v15
	v_cvt_pk_bf16_f32 v6, v43, v39
	v_cvt_pk_bf16_f32 v7, v33, v29
	v_cvt_pk_bf16_f32 v138, v10, v8
	v_cvt_pk_bf16_f32 v140, v24, v20
	v_cvt_pk_bf16_f32 v141, v16, v12
	ds_write_b128 v1, v[4:7] offset:144
	v_cvt_pk_bf16_f32 v4, v45, v41
	v_cvt_pk_bf16_f32 v5, v37, v31
	v_cvt_pk_bf16_f32 v6, v59, v55
	v_cvt_pk_bf16_f32 v7, v51, v47
	ds_write_b128 v1, v[138:141]
	v_cvt_pk_bf16_f32 v138, v26, v22
	v_cvt_pk_bf16_f32 v139, v18, v14
	v_cvt_pk_bf16_f32 v140, v42, v38
	v_cvt_pk_bf16_f32 v141, v32, v28
	ds_write_b128 v1, v[4:7] offset:160
	v_cvt_pk_bf16_f32 v4, v61, v57
	v_cvt_pk_bf16_f32 v5, v53, v49
	v_cvt_pk_bf16_f32 v6, v75, v71
	v_cvt_pk_bf16_f32 v7, v67, v63
	ds_write_b128 v1, v[138:141] offset:16
	v_cvt_pk_bf16_f32 v138, v44, v40
	v_cvt_pk_bf16_f32 v139, v36, v30
	v_cvt_pk_bf16_f32 v140, v58, v54
	v_cvt_pk_bf16_f32 v141, v50, v46
	ds_write_b128 v1, v[4:7] offset:176
	v_cvt_pk_bf16_f32 v4, v77, v73
	v_cvt_pk_bf16_f32 v5, v69, v65
	v_cvt_pk_bf16_f32 v6, v91, v87
	v_cvt_pk_bf16_f32 v7, v83, v79
	ds_write_b128 v1, v[138:141] offset:32
	v_cvt_pk_bf16_f32 v138, v60, v56
	v_cvt_pk_bf16_f32 v139, v52, v48
	v_cvt_pk_bf16_f32 v140, v74, v70
	v_cvt_pk_bf16_f32 v141, v66, v62
	ds_write_b128 v1, v[4:7] offset:192
	v_cvt_pk_bf16_f32 v4, v93, v89
	v_cvt_pk_bf16_f32 v5, v85, v81
	v_cvt_pk_bf16_f32 v6, v107, v103
	v_cvt_pk_bf16_f32 v7, v99, v95
	ds_write_b128 v1, v[138:141] offset:48
	v_cvt_pk_bf16_f32 v138, v76, v72
	v_cvt_pk_bf16_f32 v139, v68, v64
	v_cvt_pk_bf16_f32 v140, v90, v86
	v_cvt_pk_bf16_f32 v141, v82, v78
	ds_write_b128 v1, v[4:7] offset:208
	v_cvt_pk_bf16_f32 v4, v109, v105
	v_cvt_pk_bf16_f32 v5, v101, v97
	v_cvt_pk_bf16_f32 v6, v123, v119
	v_cvt_pk_bf16_f32 v7, v115, v111
	ds_write_b128 v1, v[138:141] offset:64
	v_cvt_pk_bf16_f32 v138, v92, v88
	v_cvt_pk_bf16_f32 v139, v84, v80
	v_cvt_pk_bf16_f32 v140, v106, v102
	v_cvt_pk_bf16_f32 v141, v98, v94
	ds_write_b128 v1, v[4:7] offset:224
	v_cvt_pk_bf16_f32 v4, v125, v121
	v_cvt_pk_bf16_f32 v5, v117, v113
	v_cvt_pk_bf16_f32 v6, v133, v131
	v_cvt_pk_bf16_f32 v7, v129, v127
	ds_write_b128 v1, v[138:141] offset:80
	v_cvt_pk_bf16_f32 v138, v108, v104
	v_cvt_pk_bf16_f32 v139, v100, v96
	v_cvt_pk_bf16_f32 v140, v122, v118
	v_cvt_pk_bf16_f32 v141, v114, v110
	ds_write_b128 v1, v[4:7] offset:240
	v_add_u32_e32 v4, s8, v135
	ds_write_b128 v1, v[138:141] offset:96
	v_cvt_pk_bf16_f32 v138, v124, v120
	v_cvt_pk_bf16_f32 v139, v116, v112
	v_cvt_pk_bf16_f32 v140, v132, v130
	v_cvt_pk_bf16_f32 v141, v128, v126
	v_ashrrev_i32_e32 v5, 31, v4
	v_readlane_b32 s8, v251, 3
	ds_write_b128 v1, v[138:141] offset:112
	v_lshlrev_b64 v[4:5], 13, v[4:5]
	v_readlane_b32 s9, v251, 4
	v_add_u32_e32 v1, s4, v136
	v_mov_b32_e32 v3, v34
	v_lshl_add_u64 v[8:9], s[8:9], 0, v[4:5]
	ds_read_b128 v[4:7], v1
	v_lshl_add_u64 v[8:9], s[0:1], 1, v[8:9]
	v_lshl_add_u64 v[12:13], v[8:9], 0, v[2:3]
	ds_read_b128 v[8:11], v1 offset:1024
	s_mov_b32 s0, 0x10000
	s_waitcnt lgkmcnt(0)
	global_store_dwordx4 v[12:13], v[4:7], off
	s_add_i32 s6, s6, 0x10000
	s_nop 0
	v_add_co_u32_e32 v4, vcc, s0, v12
	s_mov_b32 s0, 0x20000
	s_nop 0
	v_addc_co_u32_e32 v5, vcc, 0, v13, vcc
	global_store_dwordx4 v[4:5], v[8:11], off
	ds_read_b128 v[4:7], v1 offset:2048
	ds_read_b128 v[8:11], v1 offset:3072
	v_add_co_u32_e32 v14, vcc, s0, v12
	s_mov_b32 s0, 0x30000
	s_nop 0
	v_addc_co_u32_e32 v15, vcc, 0, v13, vcc
	s_waitcnt lgkmcnt(1)
	global_store_dwordx4 v[14:15], v[4:7], off
	s_nop 1
	v_add_co_u32_e32 v4, vcc, s0, v12
	s_mov_b32 s0, 0x40000
	s_nop 0
	v_addc_co_u32_e32 v5, vcc, 0, v13, vcc
	s_waitcnt lgkmcnt(0)
	global_store_dwordx4 v[4:5], v[8:11], off
	ds_read_b128 v[4:7], v1 offset:4096
	ds_read_b128 v[8:11], v1 offset:5120
	v_add_co_u32_e32 v14, vcc, s0, v12
	s_mov_b32 s0, 0x50000
	s_nop 0
	v_addc_co_u32_e32 v15, vcc, 0, v13, vcc
	s_waitcnt lgkmcnt(1)
	global_store_dwordx4 v[14:15], v[4:7], off
	s_nop 1
	v_add_co_u32_e32 v4, vcc, s0, v12
	s_mov_b32 s0, 0x60000
	s_nop 0
	v_addc_co_u32_e32 v5, vcc, 0, v13, vcc
	s_waitcnt lgkmcnt(0)
	global_store_dwordx4 v[4:5], v[8:11], off
	ds_read_b128 v[4:7], v1 offset:6144
	ds_read_b128 v[8:11], v1 offset:7168
	v_add_co_u32_e32 v14, vcc, s0, v12
	s_mov_b32 s0, 0x70000
	s_nop 0
	v_addc_co_u32_e32 v15, vcc, 0, v13, vcc
	s_waitcnt lgkmcnt(1)
	global_store_dwordx4 v[14:15], v[4:7], off
	s_nop 1
	v_add_co_u32_e32 v4, vcc, s0, v12
	s_mov_b32 s0, 0x80000
	s_nop 0
	v_addc_co_u32_e32 v5, vcc, 0, v13, vcc
	s_waitcnt lgkmcnt(0)
	global_store_dwordx4 v[4:5], v[8:11], off
	ds_read_b128 v[4:7], v1 offset:8192
	ds_read_b128 v[8:11], v1 offset:9216
	v_add_co_u32_e32 v14, vcc, s0, v12
	s_mov_b32 s0, 0x90000
	s_nop 0
	v_addc_co_u32_e32 v15, vcc, 0, v13, vcc
	s_waitcnt lgkmcnt(1)
	global_store_dwordx4 v[14:15], v[4:7], off
	s_nop 1
	v_add_co_u32_e32 v4, vcc, s0, v12
	s_mov_b32 s0, 0xa0000
	s_nop 0
	v_addc_co_u32_e32 v5, vcc, 0, v13, vcc
	s_waitcnt lgkmcnt(0)
	global_store_dwordx4 v[4:5], v[8:11], off
	ds_read_b128 v[4:7], v1 offset:10240
	ds_read_b128 v[8:11], v1 offset:11264
	v_add_co_u32_e32 v14, vcc, s0, v12
	s_mov_b32 s0, 0xb0000
	s_nop 0
	v_addc_co_u32_e32 v15, vcc, 0, v13, vcc
	s_waitcnt lgkmcnt(1)
	global_store_dwordx4 v[14:15], v[4:7], off
	s_nop 1
	v_add_co_u32_e32 v4, vcc, s0, v12
	s_mov_b32 s0, 0xc0000
	s_nop 0
	v_addc_co_u32_e32 v5, vcc, 0, v13, vcc
	s_waitcnt lgkmcnt(0)
	global_store_dwordx4 v[4:5], v[8:11], off
	ds_read_b128 v[4:7], v1 offset:12288
	ds_read_b128 v[8:11], v1 offset:13312
	v_add_co_u32_e32 v14, vcc, s0, v12
	s_mov_b32 s0, 0xd0000
	s_nop 0
	v_addc_co_u32_e32 v15, vcc, 0, v13, vcc
	s_waitcnt lgkmcnt(1)
	global_store_dwordx4 v[14:15], v[4:7], off
	s_nop 1
	v_add_co_u32_e32 v4, vcc, s0, v12
	s_add_i32 s0, s7, 0x200
	s_nop 0
	v_addc_co_u32_e32 v5, vcc, 0, v13, vcc
	s_waitcnt lgkmcnt(0)
	global_store_dwordx4 v[4:5], v[8:11], off
	ds_read_b128 v[4:7], v1 offset:14336
	ds_read_b128 v[8:11], v1 offset:15360
	v_add_co_u32_e32 v14, vcc, 0xe0000, v12
	s_cmpk_lt_i32 s7, 0xa80
	s_nop 0
	v_addc_co_u32_e32 v15, vcc, 0, v13, vcc
	s_waitcnt lgkmcnt(1)
	global_store_dwordx4 v[14:15], v[4:7], off
	s_mov_b32 s7, s0
	s_nop 0
	v_add_co_u32_e32 v4, vcc, 0xf0000, v12
	s_nop 1
	v_addc_co_u32_e32 v5, vcc, 0, v13, vcc
	s_waitcnt lgkmcnt(0)
	global_store_dwordx4 v[4:5], v[8:11], off
	s_cbranch_scc0 .LBB0_1506
